# QKV epilogue: merged bf16 stores issued as global (not flat) stores
# baseline (speedup 1.0000x reference)
.LBB0_722:
	s_or_b64 exec, exec, s[52:53]
	v_mov_b32_e32 v183, v182
	v_mov_b32_e32 v184, v182
	v_mov_b32_e32 v185, v182
	v_pk_mul_f32 v[128:129], v[178:179], v[184:185]
	v_pk_mul_f32 v[178:179], v[180:181], v[182:183]
	v_pk_mul_f32 v[130:131], v[54:55], v[128:129]
	v_pk_mul_f32 v[128:129], v[52:53], v[178:179]
	s_nop 0
	v_cvt_pk_bf16_f32 v234, v128, v129
	v_cvt_pk_bf16_f32 v235, v130, v131
	s_nop 1
	v_permlane16_swap_b32_e32 v232, v234
	v_permlane16_swap_b32_e32 v233, v235
	v_lshl_add_u64 v[236:237], v[190:191], 0, v[238:239]
	global_store_dwordx4 v[236:237], v[232:235], off
	s_nop 1
	s_and_saveexec_b64 s[52:53], vcc
	s_cbranch_execz .LBB0_724
	global_store_dwordx4 v[188:189], v[128:131], off offset:64 nt

.LBB0_726:
	s_or_b64 exec, exec, s[52:53]
	s_nop 0
	v_mov_b32_e32 v128, v182
	v_mov_b32_e32 v129, v182
	v_pk_mul_f32 v[128:129], v[136:137], v[128:129]
	v_pk_mul_f32 v[136:137], v[138:139], v[182:183]
	v_pk_mul_f32 v[130:131], v[50:51], v[128:129]
	v_pk_mul_f32 v[128:129], v[48:49], v[136:137]
	s_nop 0
	v_cvt_pk_bf16_f32 v234, v128, v129
	v_cvt_pk_bf16_f32 v235, v130, v131
	s_nop 1
	v_permlane16_swap_b32_e32 v232, v234
	v_permlane16_swap_b32_e32 v233, v235
	v_lshl_add_u64 v[236:237], v[190:191], 0, v[238:239]
	global_store_dwordx4 v[236:237], v[232:235], off offset:64
	s_nop 1
	s_and_saveexec_b64 s[52:53], vcc
	s_cbranch_execz .LBB0_728
	global_store_dwordx4 v[188:189], v[128:131], off offset:192 nt

.LBB0_732:
	s_or_b64 exec, exec, s[52:53]
	v_mov_b32_e32 v129, v128
	v_mov_b32_e32 v136, v128
	v_mov_b32_e32 v137, v128
	v_pk_mul_f32 v[112:113], v[124:125], v[136:137]
	v_pk_mul_f32 v[124:125], v[126:127], v[128:129]
	v_pk_mul_f32 v[114:115], v[54:55], v[112:113]
	v_pk_mul_f32 v[112:113], v[52:53], v[124:125]
	s_nop 0
	v_cvt_pk_bf16_f32 v234, v112, v113
	v_cvt_pk_bf16_f32 v235, v114, v115
	s_nop 1
	v_permlane16_swap_b32_e32 v232, v234
	v_permlane16_swap_b32_e32 v233, v235
	v_lshl_add_u64 v[236:237], v[140:141], 0, v[238:239]
	global_store_dwordx4 v[236:237], v[232:235], off
	s_nop 1
	s_and_saveexec_b64 s[52:53], vcc
	s_cbranch_execz .LBB0_734
	global_store_dwordx4 v[130:131], v[112:115], off offset:64 nt

.LBB0_736:
	s_or_b64 exec, exec, s[52:53]
	s_nop 0
	v_mov_b32_e32 v112, v128
	v_mov_b32_e32 v113, v128
	v_pk_mul_f32 v[112:113], v[116:117], v[112:113]
	v_pk_mul_f32 v[116:117], v[118:119], v[128:129]
	v_pk_mul_f32 v[114:115], v[50:51], v[112:113]
	v_pk_mul_f32 v[112:113], v[48:49], v[116:117]
	s_nop 0
	v_cvt_pk_bf16_f32 v234, v112, v113
	v_cvt_pk_bf16_f32 v235, v114, v115
	s_nop 1
	v_permlane16_swap_b32_e32 v232, v234
	v_permlane16_swap_b32_e32 v233, v235
	v_lshl_add_u64 v[236:237], v[140:141], 0, v[238:239]
	global_store_dwordx4 v[236:237], v[232:235], off offset:64
	s_nop 1
	s_and_saveexec_b64 s[52:53], vcc
	s_cbranch_execz .LBB0_738
	global_store_dwordx4 v[130:131], v[112:115], off offset:192 nt

.LBB0_742:
	s_or_b64 exec, exec, s[52:53]
	v_mov_b32_e32 v113, v112
	v_mov_b32_e32 v116, v112
	v_mov_b32_e32 v117, v112
	v_pk_mul_f32 v[96:97], v[108:109], v[116:117]
	v_pk_mul_f32 v[108:109], v[110:111], v[112:113]
	v_pk_mul_f32 v[98:99], v[54:55], v[96:97]
	v_pk_mul_f32 v[96:97], v[52:53], v[108:109]
	s_nop 0
	v_cvt_pk_bf16_f32 v234, v96, v97
	v_cvt_pk_bf16_f32 v235, v98, v99
	s_nop 1
	v_permlane16_swap_b32_e32 v232, v234
	v_permlane16_swap_b32_e32 v233, v235
	v_lshl_add_u64 v[236:237], v[120:121], 0, v[238:239]
	global_store_dwordx4 v[236:237], v[232:235], off
	s_nop 1
	s_and_saveexec_b64 s[52:53], vcc
	s_cbranch_execz .LBB0_744
	global_store_dwordx4 v[114:115], v[96:99], off offset:64 nt

.LBB0_746:
	s_or_b64 exec, exec, s[52:53]
	s_nop 0
	v_mov_b32_e32 v96, v112
	v_mov_b32_e32 v97, v112
	v_pk_mul_f32 v[96:97], v[100:101], v[96:97]
	v_pk_mul_f32 v[100:101], v[102:103], v[112:113]
	v_pk_mul_f32 v[98:99], v[50:51], v[96:97]
	v_pk_mul_f32 v[96:97], v[48:49], v[100:101]
	s_nop 0
	v_cvt_pk_bf16_f32 v234, v96, v97
	v_cvt_pk_bf16_f32 v235, v98, v99
	s_nop 1
	v_permlane16_swap_b32_e32 v232, v234
	v_permlane16_swap_b32_e32 v233, v235
	v_lshl_add_u64 v[236:237], v[120:121], 0, v[238:239]
	global_store_dwordx4 v[236:237], v[232:235], off offset:64
	s_nop 1
	s_and_saveexec_b64 s[52:53], vcc
	s_cbranch_execz .LBB0_748
	global_store_dwordx4 v[114:115], v[96:99], off offset:192 nt

.LBB0_752:
	s_or_b64 exec, exec, s[52:53]
	v_mov_b32_e32 v97, v96
	v_mov_b32_e32 v100, v96
	v_mov_b32_e32 v101, v96
	v_pk_mul_f32 v[80:81], v[92:93], v[100:101]
	v_pk_mul_f32 v[92:93], v[94:95], v[96:97]
	v_pk_mul_f32 v[82:83], v[54:55], v[80:81]
	v_pk_mul_f32 v[80:81], v[52:53], v[92:93]
	s_nop 0
	v_cvt_pk_bf16_f32 v234, v80, v81
	v_cvt_pk_bf16_f32 v235, v82, v83
	s_nop 1
	v_permlane16_swap_b32_e32 v232, v234
	v_permlane16_swap_b32_e32 v233, v235
	v_lshl_add_u64 v[236:237], v[104:105], 0, v[238:239]
	global_store_dwordx4 v[236:237], v[232:235], off
	s_nop 1
	s_and_saveexec_b64 s[52:53], vcc
	s_cbranch_execz .LBB0_754
	global_store_dwordx4 v[98:99], v[80:83], off offset:64 nt

.LBB0_756:
	s_or_b64 exec, exec, s[52:53]
	s_nop 0
	v_mov_b32_e32 v80, v96
	v_mov_b32_e32 v81, v96
	v_pk_mul_f32 v[80:81], v[84:85], v[80:81]
	v_pk_mul_f32 v[84:85], v[86:87], v[96:97]
	v_pk_mul_f32 v[82:83], v[50:51], v[80:81]
	v_pk_mul_f32 v[80:81], v[48:49], v[84:85]
	s_nop 0
	v_cvt_pk_bf16_f32 v234, v80, v81
	v_cvt_pk_bf16_f32 v235, v82, v83
	s_nop 1
	v_permlane16_swap_b32_e32 v232, v234
	v_permlane16_swap_b32_e32 v233, v235
	v_lshl_add_u64 v[236:237], v[104:105], 0, v[238:239]
	global_store_dwordx4 v[236:237], v[232:235], off offset:64
	s_nop 1
	s_and_saveexec_b64 s[52:53], vcc
	s_cbranch_execz .LBB0_758
	global_store_dwordx4 v[98:99], v[80:83], off offset:192 nt

.LBB0_762:
	s_or_b64 exec, exec, s[52:53]
	v_mov_b32_e32 v81, v80
	v_mov_b32_e32 v84, v80
	v_mov_b32_e32 v85, v80
	v_pk_mul_f32 v[64:65], v[76:77], v[84:85]
	v_pk_mul_f32 v[76:77], v[78:79], v[80:81]
	v_pk_mul_f32 v[66:67], v[54:55], v[64:65]
	v_pk_mul_f32 v[64:65], v[52:53], v[76:77]
	s_nop 0
	v_cvt_pk_bf16_f32 v234, v64, v65
	v_cvt_pk_bf16_f32 v235, v66, v67
	s_nop 1
	v_permlane16_swap_b32_e32 v232, v234
	v_permlane16_swap_b32_e32 v233, v235
	v_lshl_add_u64 v[236:237], v[88:89], 0, v[238:239]
	global_store_dwordx4 v[236:237], v[232:235], off
	s_nop 1
	s_and_saveexec_b64 s[52:53], vcc
	s_cbranch_execz .LBB0_764
	global_store_dwordx4 v[82:83], v[64:67], off offset:64 nt

.LBB0_766:
	s_or_b64 exec, exec, s[52:53]
	s_nop 0
	v_mov_b32_e32 v64, v80
	v_mov_b32_e32 v65, v80
	v_pk_mul_f32 v[64:65], v[68:69], v[64:65]
	v_pk_mul_f32 v[68:69], v[70:71], v[80:81]
	v_pk_mul_f32 v[66:67], v[50:51], v[64:65]
	v_pk_mul_f32 v[64:65], v[48:49], v[68:69]
	s_nop 0
	v_cvt_pk_bf16_f32 v234, v64, v65
	v_cvt_pk_bf16_f32 v235, v66, v67
	s_nop 1
	v_permlane16_swap_b32_e32 v232, v234
	v_permlane16_swap_b32_e32 v233, v235
	v_lshl_add_u64 v[236:237], v[88:89], 0, v[238:239]
	global_store_dwordx4 v[236:237], v[232:235], off offset:64
	s_nop 1
	s_and_saveexec_b64 s[52:53], vcc
	s_cbranch_execz .LBB0_768
	global_store_dwordx4 v[82:83], v[64:67], off offset:192 nt

.LBB0_772:
	s_or_b64 exec, exec, s[52:53]
	v_mov_b32_e32 v65, v64
	v_mov_b32_e32 v68, v64
	v_mov_b32_e32 v69, v64
	v_pk_mul_f32 v[32:33], v[44:45], v[68:69]
	v_pk_mul_f32 v[44:45], v[46:47], v[64:65]
	v_pk_mul_f32 v[34:35], v[54:55], v[32:33]
	v_pk_mul_f32 v[32:33], v[52:53], v[44:45]
	s_nop 0
	v_cvt_pk_bf16_f32 v234, v32, v33
	v_cvt_pk_bf16_f32 v235, v34, v35
	s_nop 1
	v_permlane16_swap_b32_e32 v232, v234
	v_permlane16_swap_b32_e32 v233, v235
	v_lshl_add_u64 v[236:237], v[72:73], 0, v[238:239]
	global_store_dwordx4 v[236:237], v[232:235], off
	s_nop 1
	s_and_saveexec_b64 s[52:53], vcc
	s_cbranch_execz .LBB0_774
	global_store_dwordx4 v[66:67], v[32:35], off offset:64 nt

.LBB0_776:
	s_or_b64 exec, exec, s[52:53]
	s_nop 0
	v_mov_b32_e32 v32, v64
	v_mov_b32_e32 v33, v64
	v_pk_mul_f32 v[32:33], v[36:37], v[32:33]
	v_pk_mul_f32 v[36:37], v[38:39], v[64:65]
	v_pk_mul_f32 v[34:35], v[50:51], v[32:33]
	v_pk_mul_f32 v[32:33], v[48:49], v[36:37]
	s_nop 0
	v_cvt_pk_bf16_f32 v234, v32, v33
	v_cvt_pk_bf16_f32 v235, v34, v35
	s_nop 1
	v_permlane16_swap_b32_e32 v232, v234
	v_permlane16_swap_b32_e32 v233, v235
	v_lshl_add_u64 v[236:237], v[72:73], 0, v[238:239]
	global_store_dwordx4 v[236:237], v[232:235], off offset:64
	s_nop 1
	s_and_saveexec_b64 s[52:53], vcc
	s_cbranch_execz .LBB0_778
	global_store_dwordx4 v[66:67], v[32:35], off offset:192 nt

.LBB0_782:
	s_or_b64 exec, exec, s[52:53]
	v_mov_b32_e32 v33, v32
	v_mov_b32_e32 v36, v32
	v_mov_b32_e32 v37, v32
	v_pk_mul_f32 v[16:17], v[28:29], v[36:37]
	v_pk_mul_f32 v[28:29], v[30:31], v[32:33]
	v_pk_mul_f32 v[18:19], v[54:55], v[16:17]
	v_pk_mul_f32 v[16:17], v[52:53], v[28:29]
	s_nop 0
	v_cvt_pk_bf16_f32 v234, v16, v17
	v_cvt_pk_bf16_f32 v235, v18, v19
	s_nop 1
	v_permlane16_swap_b32_e32 v232, v234
	v_permlane16_swap_b32_e32 v233, v235
	v_lshl_add_u64 v[236:237], v[40:41], 0, v[238:239]
	global_store_dwordx4 v[236:237], v[232:235], off
	s_nop 1
	s_and_saveexec_b64 s[52:53], vcc
	s_cbranch_execz .LBB0_784
	global_store_dwordx4 v[34:35], v[16:19], off offset:64 nt

.LBB0_786:
	s_or_b64 exec, exec, s[52:53]
	s_nop 0
	v_mov_b32_e32 v16, v32
	v_mov_b32_e32 v17, v32
	v_pk_mul_f32 v[16:17], v[20:21], v[16:17]
	v_pk_mul_f32 v[20:21], v[22:23], v[32:33]
	v_pk_mul_f32 v[18:19], v[50:51], v[16:17]
	v_pk_mul_f32 v[16:17], v[48:49], v[20:21]
	s_nop 0
	v_cvt_pk_bf16_f32 v234, v16, v17
	v_cvt_pk_bf16_f32 v235, v18, v19
	s_nop 1
	v_permlane16_swap_b32_e32 v232, v234
	v_permlane16_swap_b32_e32 v233, v235
	v_lshl_add_u64 v[236:237], v[40:41], 0, v[238:239]
	global_store_dwordx4 v[236:237], v[232:235], off offset:64
	s_nop 1
	s_and_saveexec_b64 s[52:53], vcc
	s_cbranch_execz .LBB0_788
	global_store_dwordx4 v[34:35], v[16:19], off offset:192 nt

.LBB0_792:
	s_or_b64 exec, exec, s[4:5]
	v_mov_b32_e32 v17, v16
	v_mov_b32_e32 v20, v16
	v_mov_b32_e32 v21, v16
	v_pk_mul_f32 v[0:1], v[12:13], v[20:21]
	v_pk_mul_f32 v[12:13], v[14:15], v[16:17]
	v_pk_mul_f32 v[2:3], v[54:55], v[0:1]
	v_pk_mul_f32 v[0:1], v[52:53], v[12:13]
	s_nop 0
	v_cvt_pk_bf16_f32 v234, v0, v1
	v_cvt_pk_bf16_f32 v235, v2, v3
	s_nop 1
	v_permlane16_swap_b32_e32 v232, v234
	v_permlane16_swap_b32_e32 v233, v235
	v_lshl_add_u64 v[236:237], v[24:25], 0, v[238:239]
	global_store_dwordx4 v[236:237], v[232:235], off
	s_nop 1
	s_and_saveexec_b64 s[4:5], vcc
	s_cbranch_execz .LBB0_794
	global_store_dwordx4 v[18:19], v[0:3], off offset:64 nt

.LBB0_796:
	s_or_b64 exec, exec, s[4:5]
	s_nop 0
	v_mov_b32_e32 v0, v16
	v_mov_b32_e32 v1, v16
	v_pk_mul_f32 v[0:1], v[4:5], v[0:1]
	v_pk_mul_f32 v[4:5], v[6:7], v[16:17]
	v_pk_mul_f32 v[2:3], v[50:51], v[0:1]
	v_pk_mul_f32 v[0:1], v[48:49], v[4:5]
	s_nop 0
	v_cvt_pk_bf16_f32 v234, v0, v1
	v_cvt_pk_bf16_f32 v235, v2, v3
	s_nop 1
	v_permlane16_swap_b32_e32 v232, v234
	v_permlane16_swap_b32_e32 v233, v235
	v_lshl_add_u64 v[236:237], v[24:25], 0, v[238:239]
	global_store_dwordx4 v[236:237], v[232:235], off offset:64
	s_nop 1
	s_and_saveexec_b64 s[4:5], vcc
	s_cbranch_execz .LBB0_798
	global_store_dwordx4 v[18:19], v[0:3], off offset:192 nt
